# attention epilogue: subln gain staged in LDS once per phase, silu(z) rows as 8 dwordx4 loads issued at epilogue start + permlane32_swap, AG stores as 8 dwordx4
# speedup vs baseline: 1.0747x; 1.0216x over previous
.LBB0_513:
	v_mov_b32_e32 v143, 0
	v_lshlrev_b64 v[4:5], 2, v[142:143]
	v_lshl_add_u64 v[6:7], s[58:59], 0, v[4:5]
	s_barrier
	v_and_b32_e32 v250, 0x7f, v1
	v_lshlrev_b32_e32 v250, 2, v250
	global_load_dword v251, v250, s[66:67]
	global_load_dword v8, v[6:7], off
	v_lshl_add_u64 v[6:7], s[60:61], 0, v[4:5]
	global_load_dword v9, v[6:7], off
	v_lshl_add_u64 v[6:7], s[62:63], 0, v[4:5]
	v_lshl_add_u64 v[4:5], s[64:65], 0, v[4:5]
	global_load_dword v6, v[6:7], off
	v_mov_b32_e32 v3, 0x86000
	global_load_dword v4, v[4:5], off
	v_mbcnt_lo_u32_b32 v5, -1, 0
	global_load_dword v3, v3, s[50:51] offset:64 sc1
	v_mbcnt_hi_u32_b32 v5, -1, v5
	v_and_b32_e32 v7, 64, v5
	v_xor_b32_e32 v10, 1, v5
	v_add_u32_e32 v7, 64, v7
	v_cmp_lt_i32_e32 vcc, v10, v7
	v_xor_b32_e32 v11, 2, v5
	v_xor_b32_e32 v12, 4, v5
	v_cndmask_b32_e32 v10, v5, v10, vcc
	v_lshlrev_b32_e32 v192, 2, v10
	v_cmp_lt_i32_e32 vcc, v11, v7
	v_xor_b32_e32 v13, 8, v5
	v_xor_b32_e32 v14, 16, v5
	v_cndmask_b32_e32 v11, v5, v11, vcc
	v_lshlrev_b32_e32 v193, 2, v11
	v_cmp_lt_i32_e32 vcc, v12, v7
	v_xor_b32_e32 v15, 32, v5
	s_add_u32 s6, s50, 0x86000
	s_addc_u32 s7, s51, 0
	v_readfirstlane_b32 s10, v1
	s_waitcnt vmcnt(3)
	v_add_u32_e32 v250, 0x22900, v250
	ds_write_b32 v250, v251
	v_mul_f32_e32 v10, v8, v9
	ds_bpermute_b32 v10, v192, v10
	s_waitcnt vmcnt(1)
	v_mul_f32_e32 v16, v6, v4
	ds_bpermute_b32 v16, v192, v16
	s_waitcnt lgkmcnt(1)
	v_fmac_f32_e32 v10, v8, v9
	v_cndmask_b32_e32 v8, v5, v12, vcc
	v_lshlrev_b32_e32 v194, 2, v8
	v_cmp_lt_i32_e32 vcc, v13, v7
	s_waitcnt lgkmcnt(0)
	v_fmac_f32_e32 v16, v6, v4
	ds_bpermute_b32 v4, v193, v10
	ds_bpermute_b32 v6, v193, v16
	s_waitcnt lgkmcnt(1)
	v_add_f32_e32 v4, v10, v4
	s_waitcnt lgkmcnt(0)
	v_add_f32_e32 v6, v16, v6
	ds_bpermute_b32 v8, v194, v4
	ds_bpermute_b32 v9, v194, v6
	v_cndmask_b32_e32 v10, v5, v13, vcc
	v_lshlrev_b32_e32 v195, 2, v10
	v_cmp_lt_i32_e32 vcc, v14, v7
	s_waitcnt lgkmcnt(1)
	v_add_f32_e32 v4, v4, v8
	s_waitcnt lgkmcnt(0)
	v_add_f32_e32 v6, v6, v9
	ds_bpermute_b32 v8, v195, v4
	ds_bpermute_b32 v9, v195, v6
	v_cndmask_b32_e32 v10, v5, v14, vcc
	v_lshlrev_b32_e32 v196, 2, v10
	v_cmp_lt_i32_e32 vcc, v15, v7
	s_waitcnt lgkmcnt(1)
	v_add_f32_e32 v4, v4, v8
	s_waitcnt lgkmcnt(0)
	v_add_f32_e32 v8, v6, v9
	ds_bpermute_b32 v6, v196, v4
	ds_bpermute_b32 v9, v196, v8
	v_cndmask_b32_e32 v5, v5, v15, vcc
	v_lshlrev_b32_e32 v197, 2, v5
	s_waitcnt lgkmcnt(1)
	v_add_f32_e32 v6, v4, v6
	s_waitcnt lgkmcnt(0)
	v_add_f32_e32 v4, v8, v9
	ds_bpermute_b32 v7, v197, v6
	ds_bpermute_b32 v5, v197, v4
	s_and_saveexec_b64 s[0:1], s[26:27]
	s_cbranch_execz .LBB0_517
	s_mov_b64 s[8:9], exec
	v_mbcnt_lo_u32_b32 v8, s8, 0
	v_mbcnt_hi_u32_b32 v8, s9, v8
	v_cmp_eq_u32_e32 vcc, 0, v8
	s_and_saveexec_b64 s[4:5], vcc
	s_cbranch_execz .LBB0_516
	s_bcnt1_i32_b64 s8, s[8:9]
	v_mov_b32_e32 v9, 0
	v_mov_b32_e32 v10, s8
	global_atomic_add v9, v9, v10, s[6:7] sc0

.LBB0_559:
	s_andn2_b64 vcc, exec, s[10:11]
	s_cbranch_vccnz .Lmy_epi_noload
	v_lshlrev_b64 v[240:241], 11, v[182:183]
	s_lshl_b32 s4, s78, 8
	v_and_b32_e32 v242, 32, v1
	v_mov_b32_e32 v243, 0
	v_lshrrev_b32_e32 v242, 2, v242
	v_or_b32_e32 v240, s4, v240
	v_lshl_add_u64 v[240:241], v[174:175], 0, v[240:241]
	v_lshl_add_u64 v[240:241], v[240:241], 0, v[242:243]
	global_load_dwordx4 v[152:155], v[240:241], off offset:0
	global_load_dwordx4 v[156:159], v[240:241], off offset:32
	global_load_dwordx4 v[160:163], v[240:241], off offset:64
	global_load_dwordx4 v[220:223], v[240:241], off offset:96
	global_load_dwordx4 v[224:227], v[240:241], off offset:128
	global_load_dwordx4 v[228:231], v[240:241], off offset:160
	global_load_dwordx4 v[232:235], v[240:241], off offset:192
	global_load_dwordx4 v[236:239], v[240:241], off offset:224

.LBB0_561:
	s_andn2_b64 vcc, exec, s[10:11]
	s_waitcnt lgkmcnt(0)
	s_barrier
	s_cbranch_vccnz .LBB0_563
	ds_read2st64_b32 v[8:9], v211 offset1:1
	ds_read2st64_b32 v[10:11], v211 offset0:2 offset1:3
	ds_read2st64_b32 v[16:17], v211 offset0:4 offset1:5
	ds_read2st64_b32 v[82:83], v211 offset0:6 offset1:7
	v_mov_b32_e32 v168, v66
	v_or_b32_e32 v4, s4, v4
	s_waitcnt lgkmcnt(3)
	v_mov_b32_e32 v7, v8
	v_pk_mul_f32 v[12:13], v[168:169], v[6:7]
	v_mov_b32_e32 v168, v67
	v_mov_b32_e32 v7, v9
	v_pk_mul_f32 v[8:9], v[168:169], v[6:7]
	v_mov_b32_e32 v168, v68
	s_waitcnt lgkmcnt(2)
	v_mov_b32_e32 v7, v10
	v_sub_f32_e32 v14, v8, v9
	v_pk_mul_f32 v[8:9], v[168:169], v[6:7]
	v_mov_b32_e32 v168, v69
	v_mov_b32_e32 v7, v11
	v_pk_mul_f32 v[10:11], v[168:169], v[6:7]
	v_mov_b32_e32 v168, v70
	s_waitcnt lgkmcnt(1)
	v_mov_b32_e32 v7, v16
	v_sub_f32_e32 v8, v8, v9
	v_sub_f32_e32 v9, v10, v11
	v_pk_mul_f32 v[10:11], v[168:169], v[6:7]
	v_mov_b32_e32 v168, v71
	v_mov_b32_e32 v7, v17
	v_sub_f32_e32 v2, v10, v11
	v_pk_mul_f32 v[10:11], v[168:169], v[6:7]
	v_mov_b32_e32 v168, v72
	s_waitcnt lgkmcnt(0)
	v_mov_b32_e32 v7, v82
	v_pk_mul_f32 v[16:17], v[168:169], v[6:7]
	v_mov_b32_e32 v168, v73
	v_mov_b32_e32 v7, v83
	v_sub_f32_e32 v10, v10, v11
	v_sub_f32_e32 v11, v16, v17
	v_pk_mul_f32 v[16:17], v[168:169], v[6:7]
	v_sub_f32_e32 v13, v12, v13
	v_sub_f32_e32 v12, v16, v17
	ds_read2st64_b32 v[16:17], v211 offset0:8 offset1:9
	ds_read2st64_b32 v[72:73], v211 offset0:10 offset1:11
	ds_read2st64_b32 v[82:83], v211 offset0:12 offset1:13
	ds_read2st64_b32 v[84:85], v211 offset0:14 offset1:15
	v_mov_b32_e32 v168, v74
	s_waitcnt lgkmcnt(3)
	v_mov_b32_e32 v7, v16
	v_pk_mul_f32 v[66:67], v[168:169], v[6:7]
	v_mov_b32_e32 v168, v75
	v_mov_b32_e32 v7, v17
	v_pk_mul_f32 v[16:17], v[168:169], v[6:7]
	v_mov_b32_e32 v168, v76
	s_waitcnt lgkmcnt(2)
	v_mov_b32_e32 v7, v72
	v_sub_f32_e32 v70, v16, v17
	v_pk_mul_f32 v[16:17], v[168:169], v[6:7]
	v_mov_b32_e32 v168, v77
	v_mov_b32_e32 v7, v73
	ds_read2st64_b32 v[74:75], v211 offset0:16 offset1:17
	v_sub_f32_e32 v69, v66, v67
	v_sub_f32_e32 v67, v16, v17
	v_pk_mul_f32 v[16:17], v[168:169], v[6:7]
	v_mov_b32_e32 v168, v78
	s_waitcnt lgkmcnt(2)
	v_mov_b32_e32 v7, v82
	v_sub_f32_e32 v68, v16, v17
	v_pk_mul_f32 v[16:17], v[168:169], v[6:7]
	v_mov_b32_e32 v168, v79
	v_mov_b32_e32 v7, v83
	v_sub_f32_e32 v15, v16, v17
	v_pk_mul_f32 v[16:17], v[168:169], v[6:7]
	v_mov_b32_e32 v168, v80
	s_waitcnt lgkmcnt(1)
	v_mov_b32_e32 v7, v84
	v_pk_mul_f32 v[72:73], v[168:169], v[6:7]
	v_mov_b32_e32 v168, v81
	v_mov_b32_e32 v7, v85
	ds_read2st64_b32 v[76:77], v211 offset0:18 offset1:19
	ds_read2st64_b32 v[78:79], v211 offset0:20 offset1:21
	ds_read2st64_b32 v[80:81], v211 offset0:22 offset1:23
	v_sub_f32_e32 v16, v16, v17
	v_sub_f32_e32 v17, v72, v73
	v_pk_mul_f32 v[72:73], v[168:169], v[6:7]
	v_mov_b32_e32 v168, v50
	s_waitcnt lgkmcnt(3)
	v_mov_b32_e32 v7, v74
	v_sub_f32_e32 v66, v72, v73
	v_pk_mul_f32 v[72:73], v[168:169], v[6:7]
	v_mov_b32_e32 v168, v51
	v_mov_b32_e32 v7, v75
	v_pk_mul_f32 v[50:51], v[168:169], v[6:7]
	v_mov_b32_e32 v168, v52
	s_waitcnt lgkmcnt(2)
	v_mov_b32_e32 v7, v76
	v_sub_f32_e32 v74, v50, v51
	v_pk_mul_f32 v[50:51], v[168:169], v[6:7]
	v_mov_b32_e32 v168, v53
	v_mov_b32_e32 v7, v77
	v_sub_f32_e32 v71, v50, v51
	v_pk_mul_f32 v[50:51], v[168:169], v[6:7]
	v_mov_b32_e32 v168, v54
	s_waitcnt lgkmcnt(1)
	v_mov_b32_e32 v7, v78
	v_sub_f32_e32 v73, v72, v73
	v_sub_f32_e32 v72, v50, v51
	v_pk_mul_f32 v[50:51], v[168:169], v[6:7]
	v_mov_b32_e32 v168, v55
	v_mov_b32_e32 v7, v79
	v_pk_mul_f32 v[52:53], v[168:169], v[6:7]
	v_mov_b32_e32 v168, v56
	s_waitcnt lgkmcnt(0)
	v_mov_b32_e32 v7, v80
	v_sub_f32_e32 v50, v50, v51
	v_sub_f32_e32 v51, v52, v53
	v_pk_mul_f32 v[52:53], v[168:169], v[6:7]
	v_mov_b32_e32 v168, v57
	v_mov_b32_e32 v7, v81
	v_pk_mul_f32 v[54:55], v[168:169], v[6:7]
	v_sub_f32_e32 v52, v52, v53
	v_sub_f32_e32 v53, v54, v55
	ds_read2st64_b32 v[54:55], v211 offset0:24 offset1:25
	ds_read2st64_b32 v[56:57], v211 offset0:26 offset1:27
	ds_read2st64_b32 v[78:79], v211 offset0:28 offset1:29
	ds_read2st64_b32 v[80:81], v211 offset0:30 offset1:31
	v_mov_b32_e32 v168, v58
	s_waitcnt lgkmcnt(3)
	v_mov_b32_e32 v7, v54
	v_pk_mul_f32 v[76:77], v[168:169], v[6:7]
	v_mov_b32_e32 v168, v59
	v_mov_b32_e32 v7, v55
	v_pk_mul_f32 v[54:55], v[168:169], v[6:7]
	v_mov_b32_e32 v168, v60
	s_waitcnt lgkmcnt(2)
	v_mov_b32_e32 v7, v56
	v_sub_f32_e32 v75, v76, v77
	v_sub_f32_e32 v76, v54, v55
	v_pk_mul_f32 v[54:55], v[168:169], v[6:7]
	v_mov_b32_e32 v168, v61
	v_mov_b32_e32 v7, v57
	v_sub_f32_e32 v58, v54, v55
	v_pk_mul_f32 v[54:55], v[168:169], v[6:7]
	v_mov_b32_e32 v168, v62
	s_waitcnt lgkmcnt(1)
	v_mov_b32_e32 v7, v78
	v_sub_f32_e32 v59, v54, v55
	v_pk_mul_f32 v[54:55], v[168:169], v[6:7]
	v_mov_b32_e32 v168, v63
	v_mov_b32_e32 v7, v79
	v_pk_mul_f32 v[56:57], v[168:169], v[6:7]
	v_mov_b32_e32 v168, v64
	s_waitcnt lgkmcnt(0)
	v_mov_b32_e32 v7, v80
	v_sub_f32_e32 v54, v54, v55
	v_sub_f32_e32 v55, v56, v57
	v_pk_mul_f32 v[56:57], v[168:169], v[6:7]
	v_mov_b32_e32 v168, v65
	v_mov_b32_e32 v7, v81
	v_pk_mul_f32 v[60:61], v[168:169], v[6:7]
	v_sub_f32_e32 v56, v56, v57
	v_sub_f32_e32 v57, v60, v61
	ds_read2st64_b32 v[60:61], v211 offset0:32 offset1:33
	ds_read2st64_b32 v[64:65], v211 offset0:34 offset1:35
	ds_read2st64_b32 v[78:79], v211 offset0:36 offset1:37
	ds_read2st64_b32 v[80:81], v211 offset0:38 offset1:39
	v_mov_b32_e32 v168, v34
	v_mul_f32_e32 v77, v13, v13
	v_fmac_f32_e32 v77, v14, v14
	s_waitcnt lgkmcnt(3)
	v_mov_b32_e32 v7, v60
	v_pk_mul_f32 v[62:63], v[168:169], v[6:7]
	v_mov_b32_e32 v168, v35
	v_mov_b32_e32 v7, v61
	v_pk_mul_f32 v[34:35], v[168:169], v[6:7]
	v_mov_b32_e32 v168, v36
	s_waitcnt lgkmcnt(2)
	v_mov_b32_e32 v7, v64
	v_sub_f32_e32 v62, v62, v63
	v_sub_f32_e32 v63, v34, v35
	v_pk_mul_f32 v[34:35], v[168:169], v[6:7]
	v_mov_b32_e32 v168, v37
	v_mov_b32_e32 v7, v65
	v_sub_f32_e32 v60, v34, v35
	v_pk_mul_f32 v[34:35], v[168:169], v[6:7]
	v_mov_b32_e32 v168, v38
	s_waitcnt lgkmcnt(1)
	v_mov_b32_e32 v7, v78
	v_sub_f32_e32 v61, v34, v35
	v_pk_mul_f32 v[34:35], v[168:169], v[6:7]
	v_mov_b32_e32 v168, v39
	v_mov_b32_e32 v7, v79
	v_pk_mul_f32 v[36:37], v[168:169], v[6:7]
	v_mov_b32_e32 v168, v40
	s_waitcnt lgkmcnt(0)
	v_mov_b32_e32 v7, v80
	v_sub_f32_e32 v34, v34, v35
	v_sub_f32_e32 v35, v36, v37
	v_pk_mul_f32 v[36:37], v[168:169], v[6:7]
	v_mov_b32_e32 v168, v41
	v_mov_b32_e32 v7, v81
	v_pk_mul_f32 v[38:39], v[168:169], v[6:7]
	v_sub_f32_e32 v36, v36, v37
	v_sub_f32_e32 v37, v38, v39
	ds_read2st64_b32 v[38:39], v211 offset0:40 offset1:41
	ds_read2st64_b32 v[40:41], v211 offset0:42 offset1:43
	ds_read2st64_b32 v[78:79], v211 offset0:44 offset1:45
	ds_read2st64_b32 v[80:81], v211 offset0:46 offset1:47
	v_mov_b32_e32 v168, v42
	v_fmac_f32_e32 v77, v8, v8
	v_fmac_f32_e32 v77, v9, v9
	s_waitcnt lgkmcnt(3)
	v_mov_b32_e32 v7, v38
	v_pk_mul_f32 v[64:65], v[168:169], v[6:7]
	v_mov_b32_e32 v168, v43
	v_mov_b32_e32 v7, v39
	v_pk_mul_f32 v[38:39], v[168:169], v[6:7]
	v_mov_b32_e32 v168, v44
	s_waitcnt lgkmcnt(2)
	v_mov_b32_e32 v7, v40
	v_sub_f32_e32 v64, v64, v65
	v_sub_f32_e32 v65, v38, v39
	v_pk_mul_f32 v[38:39], v[168:169], v[6:7]
	v_mov_b32_e32 v168, v45
	v_mov_b32_e32 v7, v41
	v_sub_f32_e32 v42, v38, v39
	v_pk_mul_f32 v[38:39], v[168:169], v[6:7]
	v_mov_b32_e32 v168, v46
	s_waitcnt lgkmcnt(1)
	v_mov_b32_e32 v7, v78
	v_sub_f32_e32 v43, v38, v39
	v_pk_mul_f32 v[38:39], v[168:169], v[6:7]
	v_mov_b32_e32 v168, v47
	v_mov_b32_e32 v7, v79
	v_pk_mul_f32 v[40:41], v[168:169], v[6:7]
	v_mov_b32_e32 v168, v48
	s_waitcnt lgkmcnt(0)
	v_mov_b32_e32 v7, v80
	v_sub_f32_e32 v38, v38, v39
	v_sub_f32_e32 v39, v40, v41
	v_pk_mul_f32 v[40:41], v[168:169], v[6:7]
	v_mov_b32_e32 v168, v49
	v_mov_b32_e32 v7, v81
	v_pk_mul_f32 v[44:45], v[168:169], v[6:7]
	v_sub_f32_e32 v40, v40, v41
	v_sub_f32_e32 v41, v44, v45
	ds_read2st64_b32 v[44:45], v211 offset0:48 offset1:49
	ds_read2st64_b32 v[48:49], v211 offset0:50 offset1:51
	ds_read2st64_b32 v[78:79], v211 offset0:52 offset1:53
	ds_read2st64_b32 v[80:81], v211 offset0:54 offset1:55
	v_mov_b32_e32 v168, v18
	v_fmac_f32_e32 v77, v2, v2
	v_fmac_f32_e32 v77, v10, v10
	s_waitcnt lgkmcnt(3)
	v_mov_b32_e32 v7, v44
	v_pk_mul_f32 v[46:47], v[168:169], v[6:7]
	v_mov_b32_e32 v168, v19
	v_mov_b32_e32 v7, v45
	v_pk_mul_f32 v[18:19], v[168:169], v[6:7]
	v_mov_b32_e32 v168, v20
	s_waitcnt lgkmcnt(2)
	v_mov_b32_e32 v7, v48
	v_sub_f32_e32 v46, v46, v47
	v_sub_f32_e32 v47, v18, v19
	v_pk_mul_f32 v[18:19], v[168:169], v[6:7]
	v_mov_b32_e32 v168, v21
	v_mov_b32_e32 v7, v49
	v_sub_f32_e32 v44, v18, v19
	v_pk_mul_f32 v[18:19], v[168:169], v[6:7]
	v_mov_b32_e32 v168, v22
	s_waitcnt lgkmcnt(1)
	v_mov_b32_e32 v7, v78
	v_sub_f32_e32 v45, v18, v19
	v_pk_mul_f32 v[18:19], v[168:169], v[6:7]
	v_mov_b32_e32 v168, v23
	v_mov_b32_e32 v7, v79
	v_pk_mul_f32 v[20:21], v[168:169], v[6:7]
	v_mov_b32_e32 v168, v24
	s_waitcnt lgkmcnt(0)
	v_mov_b32_e32 v7, v80
	v_sub_f32_e32 v18, v18, v19
	v_sub_f32_e32 v19, v20, v21
	v_pk_mul_f32 v[20:21], v[168:169], v[6:7]
	v_mov_b32_e32 v168, v25
	v_mov_b32_e32 v7, v81
	v_pk_mul_f32 v[22:23], v[168:169], v[6:7]
	v_fmac_f32_e32 v77, v11, v11
	v_sub_f32_e32 v20, v20, v21
	v_sub_f32_e32 v21, v22, v23
	ds_read2st64_b32 v[22:23], v211 offset0:56 offset1:57
	v_fmac_f32_e32 v77, v12, v12
	v_fmac_f32_e32 v77, v69, v69
	v_fmac_f32_e32 v77, v70, v70
	v_fmac_f32_e32 v77, v67, v67
	ds_read2st64_b32 v[24:25], v211 offset0:58 offset1:59
	ds_read2st64_b32 v[48:49], v211 offset0:60 offset1:61
	ds_read2st64_b32 v[78:79], v211 offset0:62 offset1:63
	v_fmac_f32_e32 v77, v68, v68
	v_mov_b32_e32 v168, v26
	s_waitcnt lgkmcnt(3)
	v_mov_b32_e32 v7, v22
	v_fmac_f32_e32 v77, v15, v15
	v_pk_mul_f32 v[80:81], v[168:169], v[6:7]
	v_mov_b32_e32 v168, v27
	v_mov_b32_e32 v7, v23
	v_fmac_f32_e32 v77, v16, v16
	v_pk_mul_f32 v[22:23], v[168:169], v[6:7]
	v_mov_b32_e32 v168, v28
	s_waitcnt lgkmcnt(2)
	v_mov_b32_e32 v7, v24
	v_fmac_f32_e32 v77, v17, v17
	v_sub_f32_e32 v27, v22, v23
	v_pk_mul_f32 v[22:23], v[168:169], v[6:7]
	v_mov_b32_e32 v168, v29
	v_mov_b32_e32 v7, v25
	v_fmac_f32_e32 v77, v66, v66
	v_sub_f32_e32 v24, v22, v23
	v_pk_mul_f32 v[22:23], v[168:169], v[6:7]
	v_mov_b32_e32 v168, v30
	s_waitcnt lgkmcnt(1)
	v_mov_b32_e32 v7, v48
	v_fmac_f32_e32 v77, v73, v73
	v_sub_f32_e32 v25, v22, v23
	v_pk_mul_f32 v[22:23], v[168:169], v[6:7]
	v_mov_b32_e32 v168, v31
	v_mov_b32_e32 v7, v49
	v_fmac_f32_e32 v77, v74, v74
	v_pk_mul_f32 v[28:29], v[168:169], v[6:7]
	v_fmac_f32_e32 v77, v71, v71
	v_lshlrev_b64 v[48:49], 1, v[4:5]
	v_sub_f32_e32 v22, v22, v23
	v_sub_f32_e32 v23, v28, v29
	s_waitcnt lgkmcnt(0)
	v_pk_mul_f32 v[28:29], v[172:173], v[78:79]
	v_fmac_f32_e32 v77, v72, v72
	v_lshl_add_u64 v[4:5], v[174:175], 0, v[48:49]
	v_pk_fma_f32 v[6:7], v[32:33], v[6:7], v[28:29] op_sel_hi:[1,0,1] neg_lo:[0,0,1] neg_hi:[0,0,1]
	v_fmac_f32_e32 v77, v50, v50
	v_lshlrev_b32_e32 v246, 1, v242
	v_add_u32_e32 v246, 0x22900, v246
	ds_read_b128 v[88:91], v246 offset:0
	ds_read_b128 v[92:95], v246 offset:32
	ds_read_b128 v[96:99], v246 offset:64
	ds_read_b128 v[100:103], v246 offset:96
	ds_read_b128 v[104:107], v246 offset:128
	ds_read_b128 v[108:111], v246 offset:160
	ds_read_b128 v[112:115], v246 offset:192
	ds_read_b128 v[116:119], v246 offset:224
	ds_read_b128 v[120:123], v246 offset:256
	ds_read_b128 v[124:127], v246 offset:288
	ds_read_b128 v[128:131], v246 offset:320
	ds_read_b128 v[132:135], v246 offset:352
	ds_read_b128 v[136:139], v246 offset:384
	ds_read_b128 v[140:143], v246 offset:416
	ds_read_b128 v[144:147], v246 offset:448
	ds_read_b128 v[148:151], v246 offset:480
	v_fmac_f32_e32 v77, v51, v51
	v_fmac_f32_e32 v77, v52, v52
	v_fmac_f32_e32 v77, v53, v53
	v_fmac_f32_e32 v77, v75, v75
	v_fmac_f32_e32 v77, v76, v76
	v_fmac_f32_e32 v77, v58, v58
	v_fmac_f32_e32 v77, v59, v59
	v_fmac_f32_e32 v77, v54, v54
	v_fmac_f32_e32 v77, v55, v55
	v_fmac_f32_e32 v77, v56, v56
	v_fmac_f32_e32 v77, v57, v57
	v_fmac_f32_e32 v77, v62, v62
	v_fmac_f32_e32 v77, v63, v63
	v_fmac_f32_e32 v77, v60, v60
	v_fmac_f32_e32 v77, v61, v61
	v_fmac_f32_e32 v77, v34, v34
	v_fmac_f32_e32 v77, v35, v35
	v_fmac_f32_e32 v77, v36, v36
	v_fmac_f32_e32 v77, v37, v37
	v_fmac_f32_e32 v77, v64, v64
	v_fmac_f32_e32 v77, v65, v65
	v_fmac_f32_e32 v77, v42, v42
	v_fmac_f32_e32 v77, v43, v43
	v_fmac_f32_e32 v77, v38, v38
	v_fmac_f32_e32 v77, v39, v39
	v_fmac_f32_e32 v77, v40, v40
	v_fmac_f32_e32 v77, v41, v41
	v_fmac_f32_e32 v77, v46, v46
	v_fmac_f32_e32 v77, v47, v47
	v_fmac_f32_e32 v77, v44, v44
	v_fmac_f32_e32 v77, v45, v45
	v_fmac_f32_e32 v77, v18, v18
	v_fmac_f32_e32 v77, v19, v19
	v_fmac_f32_e32 v77, v20, v20
	v_sub_f32_e32 v26, v80, v81
	v_fmac_f32_e32 v77, v21, v21
	v_fmac_f32_e32 v77, v26, v26
	v_fmac_f32_e32 v77, v27, v27
	v_fmac_f32_e32 v77, v24, v24
	v_fmac_f32_e32 v77, v25, v25
	v_fmac_f32_e32 v77, v22, v22
	v_pk_mul_f32 v[32:33], v[6:7], v[6:7]
	v_fmac_f32_e32 v77, v23, v23
	v_add_f32_e32 v32, v77, v32
	v_add_f32_e32 v32, v32, v33
	ds_bpermute_b32 v33, v197, v32
	s_waitcnt lgkmcnt(0)
	v_add_f32_e32 v32, v32, v33
	v_fmamk_f32 v32, v32, 0x3c000000, v214
	v_mul_f32_e32 v33, 0x4f800000, v32
	v_cmp_gt_f32_e32 vcc, s71, v32
	s_nop 1
	v_cndmask_b32_e32 v32, v32, v33, vcc
	v_sqrt_f32_e32 v33, v32
	s_nop 0
	v_add_u32_e32 v77, -1, v33
	v_fma_f32 v80, -v77, v33, v32
	v_cmp_ge_f32_e64 s[4:5], 0, v80
	v_add_u32_e32 v80, 1, v33
	s_nop 0
	v_cndmask_b32_e64 v77, v33, v77, s[4:5]
	v_fma_f32 v33, -v80, v33, v32
	v_cmp_lt_f32_e64 s[4:5], 0, v33
	s_nop 1
	v_cndmask_b32_e64 v33, v77, v80, s[4:5]
	v_mul_f32_e32 v77, 0x37800000, v33
	v_cndmask_b32_e32 v33, v33, v77, vcc
	v_cmp_class_f32_e32 vcc, v32, v200
	s_nop 1
	v_cndmask_b32_e32 v32, v33, v32, vcc
	v_div_scale_f32 v33, s[4:5], v32, v32, s76
	v_rcp_f32_e32 v77, v33
	s_nop 0
	v_fma_f32 v80, -v33, v77, 1.0
	v_fmac_f32_e32 v77, v80, v77
	v_div_scale_f32 v80, vcc, s76, v32, s76
	v_mul_f32_e32 v81, v80, v77
	v_fma_f32 v82, -v33, v81, v80
	v_fmac_f32_e32 v81, v82, v77
	v_fma_f32 v33, -v33, v81, v80
	v_div_fmas_f32 v33, v33, v77, v81
	v_div_fixup_f32 v77, v33, v32, s76
	v_lshl_add_u64 v[244:245], v[176:177], 0, v[48:49]
	v_lshl_add_u64 v[244:245], v[244:245], 0, v[242:243]
	s_waitcnt vmcnt(7)
	v_permlane32_swap_b32_e32 v152, v154
	v_permlane32_swap_b32_e32 v153, v155
	v_mul_f32_e32 v13, v13, v77
	v_mul_f32_e32 v14, v14, v77
	v_lshlrev_b32_e32 v247, 16, v152
	v_mul_f32_e32 v13, v88, v13
	v_mul_f32_e32 v14, v89, v14
	v_and_b32_e32 v152, 0xffff0000, v152
	v_mul_f32_e32 v13, v13, v247
	v_mul_f32_e32 v14, v14, v152
	v_cvt_pk_bf16_f32 v152, v13, v14
	v_mul_f32_e32 v8, v8, v77
	v_mul_f32_e32 v9, v9, v77
	v_lshlrev_b32_e32 v247, 16, v153
	v_mul_f32_e32 v8, v90, v8
	v_mul_f32_e32 v9, v91, v9
	v_and_b32_e32 v153, 0xffff0000, v153
	v_mul_f32_e32 v8, v8, v247
	v_mul_f32_e32 v9, v9, v153
	v_cvt_pk_bf16_f32 v153, v8, v9
	v_mul_f32_e32 v2, v2, v77
	v_mul_f32_e32 v10, v10, v77
	v_lshlrev_b32_e32 v247, 16, v154
	v_mul_f32_e32 v2, v92, v2
	v_mul_f32_e32 v10, v93, v10
	v_and_b32_e32 v154, 0xffff0000, v154
	v_mul_f32_e32 v2, v2, v247
	v_mul_f32_e32 v10, v10, v154
	v_cvt_pk_bf16_f32 v154, v2, v10
	v_mul_f32_e32 v11, v11, v77
	v_mul_f32_e32 v12, v12, v77
	v_lshlrev_b32_e32 v247, 16, v155
	v_mul_f32_e32 v11, v94, v11
	v_mul_f32_e32 v12, v95, v12
	v_and_b32_e32 v155, 0xffff0000, v155
	v_mul_f32_e32 v11, v11, v247
	v_mul_f32_e32 v12, v12, v155
	v_cvt_pk_bf16_f32 v155, v11, v12
	s_nop 1
	v_permlane32_swap_b32_e32 v152, v154
	v_permlane32_swap_b32_e32 v153, v155
	global_store_dwordx4 v[244:245], v[152:155], off offset:0
	s_waitcnt vmcnt(7)
	v_permlane32_swap_b32_e32 v156, v158
	v_permlane32_swap_b32_e32 v157, v159
	v_mul_f32_e32 v69, v69, v77
	v_mul_f32_e32 v70, v70, v77
	v_lshlrev_b32_e32 v247, 16, v156
	v_mul_f32_e32 v69, v96, v69
	v_mul_f32_e32 v70, v97, v70
	v_and_b32_e32 v156, 0xffff0000, v156
	v_mul_f32_e32 v69, v69, v247
	v_mul_f32_e32 v70, v70, v156
	v_cvt_pk_bf16_f32 v156, v69, v70
	v_mul_f32_e32 v67, v67, v77
	v_mul_f32_e32 v68, v68, v77
	v_lshlrev_b32_e32 v247, 16, v157
	v_mul_f32_e32 v67, v98, v67
	v_mul_f32_e32 v68, v99, v68
	v_and_b32_e32 v157, 0xffff0000, v157
	v_mul_f32_e32 v67, v67, v247
	v_mul_f32_e32 v68, v68, v157
	v_cvt_pk_bf16_f32 v157, v67, v68
	v_mul_f32_e32 v15, v15, v77
	v_mul_f32_e32 v16, v16, v77
	v_lshlrev_b32_e32 v247, 16, v158
	v_mul_f32_e32 v15, v100, v15
	v_mul_f32_e32 v16, v101, v16
	v_and_b32_e32 v158, 0xffff0000, v158
	v_mul_f32_e32 v15, v15, v247
	v_mul_f32_e32 v16, v16, v158
	v_cvt_pk_bf16_f32 v158, v15, v16
	v_mul_f32_e32 v17, v17, v77
	v_mul_f32_e32 v66, v66, v77
	v_lshlrev_b32_e32 v247, 16, v159
	v_mul_f32_e32 v17, v102, v17
	v_mul_f32_e32 v66, v103, v66
	v_and_b32_e32 v159, 0xffff0000, v159
	v_mul_f32_e32 v17, v17, v247
	v_mul_f32_e32 v66, v66, v159
	v_cvt_pk_bf16_f32 v159, v17, v66
	s_nop 1
	v_permlane32_swap_b32_e32 v156, v158
	v_permlane32_swap_b32_e32 v157, v159
	global_store_dwordx4 v[244:245], v[156:159], off offset:32
	s_waitcnt vmcnt(7)
	v_permlane32_swap_b32_e32 v160, v162
	v_permlane32_swap_b32_e32 v161, v163
	v_mul_f32_e32 v73, v73, v77
	v_mul_f32_e32 v74, v74, v77
	v_lshlrev_b32_e32 v247, 16, v160
	v_mul_f32_e32 v73, v104, v73
	v_mul_f32_e32 v74, v105, v74
	v_and_b32_e32 v160, 0xffff0000, v160
	v_mul_f32_e32 v73, v73, v247
	v_mul_f32_e32 v74, v74, v160
	v_cvt_pk_bf16_f32 v160, v73, v74
	v_mul_f32_e32 v71, v71, v77
	v_mul_f32_e32 v72, v72, v77
	v_lshlrev_b32_e32 v247, 16, v161
	v_mul_f32_e32 v71, v106, v71
	v_mul_f32_e32 v72, v107, v72
	v_and_b32_e32 v161, 0xffff0000, v161
	v_mul_f32_e32 v71, v71, v247
	v_mul_f32_e32 v72, v72, v161
	v_cvt_pk_bf16_f32 v161, v71, v72
	v_mul_f32_e32 v50, v50, v77
	v_mul_f32_e32 v51, v51, v77
	v_lshlrev_b32_e32 v247, 16, v162
	v_mul_f32_e32 v50, v108, v50
	v_mul_f32_e32 v51, v109, v51
	v_and_b32_e32 v162, 0xffff0000, v162
	v_mul_f32_e32 v50, v50, v247
	v_mul_f32_e32 v51, v51, v162
	v_cvt_pk_bf16_f32 v162, v50, v51
	v_mul_f32_e32 v52, v52, v77
	v_mul_f32_e32 v53, v53, v77
	v_lshlrev_b32_e32 v247, 16, v163
	v_mul_f32_e32 v52, v110, v52
	v_mul_f32_e32 v53, v111, v53
	v_and_b32_e32 v163, 0xffff0000, v163
	v_mul_f32_e32 v52, v52, v247
	v_mul_f32_e32 v53, v53, v163
	v_cvt_pk_bf16_f32 v163, v52, v53
	s_nop 1
	v_permlane32_swap_b32_e32 v160, v162
	v_permlane32_swap_b32_e32 v161, v163
	global_store_dwordx4 v[244:245], v[160:163], off offset:64
	s_waitcnt vmcnt(7)
	v_permlane32_swap_b32_e32 v220, v222
	v_permlane32_swap_b32_e32 v221, v223
	v_mul_f32_e32 v75, v75, v77
	v_mul_f32_e32 v76, v76, v77
	v_lshlrev_b32_e32 v247, 16, v220
	v_mul_f32_e32 v75, v112, v75
	v_mul_f32_e32 v76, v113, v76
	v_and_b32_e32 v220, 0xffff0000, v220
	v_mul_f32_e32 v75, v75, v247
	v_mul_f32_e32 v76, v76, v220
	v_cvt_pk_bf16_f32 v220, v75, v76
	v_mul_f32_e32 v58, v58, v77
	v_mul_f32_e32 v59, v59, v77
	v_lshlrev_b32_e32 v247, 16, v221
	v_mul_f32_e32 v58, v114, v58
	v_mul_f32_e32 v59, v115, v59
	v_and_b32_e32 v221, 0xffff0000, v221
	v_mul_f32_e32 v58, v58, v247
	v_mul_f32_e32 v59, v59, v221
	v_cvt_pk_bf16_f32 v221, v58, v59
	v_mul_f32_e32 v54, v54, v77
	v_mul_f32_e32 v55, v55, v77
	v_lshlrev_b32_e32 v247, 16, v222
	v_mul_f32_e32 v54, v116, v54
	v_mul_f32_e32 v55, v117, v55
	v_and_b32_e32 v222, 0xffff0000, v222
	v_mul_f32_e32 v54, v54, v247
	v_mul_f32_e32 v55, v55, v222
	v_cvt_pk_bf16_f32 v222, v54, v55
	v_mul_f32_e32 v56, v56, v77
	v_mul_f32_e32 v57, v57, v77
	v_lshlrev_b32_e32 v247, 16, v223
	v_mul_f32_e32 v56, v118, v56
	v_mul_f32_e32 v57, v119, v57
	v_and_b32_e32 v223, 0xffff0000, v223
	v_mul_f32_e32 v56, v56, v247
	v_mul_f32_e32 v57, v57, v223
	v_cvt_pk_bf16_f32 v223, v56, v57
	s_nop 1
	v_permlane32_swap_b32_e32 v220, v222
	v_permlane32_swap_b32_e32 v221, v223
	global_store_dwordx4 v[244:245], v[220:223], off offset:96
	s_waitcnt vmcnt(7)
	v_permlane32_swap_b32_e32 v224, v226
	v_permlane32_swap_b32_e32 v225, v227
	v_mul_f32_e32 v62, v62, v77
	v_mul_f32_e32 v63, v63, v77
	v_lshlrev_b32_e32 v247, 16, v224
	v_mul_f32_e32 v62, v120, v62
	v_mul_f32_e32 v63, v121, v63
	v_and_b32_e32 v224, 0xffff0000, v224
	v_mul_f32_e32 v62, v62, v247
	v_mul_f32_e32 v63, v63, v224
	v_cvt_pk_bf16_f32 v224, v62, v63
	v_mul_f32_e32 v60, v60, v77
	v_mul_f32_e32 v61, v61, v77
	v_lshlrev_b32_e32 v247, 16, v225
	v_mul_f32_e32 v60, v122, v60
	v_mul_f32_e32 v61, v123, v61
	v_and_b32_e32 v225, 0xffff0000, v225
	v_mul_f32_e32 v60, v60, v247
	v_mul_f32_e32 v61, v61, v225
	v_cvt_pk_bf16_f32 v225, v60, v61
	v_mul_f32_e32 v34, v34, v77
	v_mul_f32_e32 v35, v35, v77
	v_lshlrev_b32_e32 v247, 16, v226
	v_mul_f32_e32 v34, v124, v34
	v_mul_f32_e32 v35, v125, v35
	v_and_b32_e32 v226, 0xffff0000, v226
	v_mul_f32_e32 v34, v34, v247
	v_mul_f32_e32 v35, v35, v226
	v_cvt_pk_bf16_f32 v226, v34, v35
	v_mul_f32_e32 v36, v36, v77
	v_mul_f32_e32 v37, v37, v77
	v_lshlrev_b32_e32 v247, 16, v227
	v_mul_f32_e32 v36, v126, v36
	v_mul_f32_e32 v37, v127, v37
	v_and_b32_e32 v227, 0xffff0000, v227
	v_mul_f32_e32 v36, v36, v247
	v_mul_f32_e32 v37, v37, v227
	v_cvt_pk_bf16_f32 v227, v36, v37
	s_nop 1
	v_permlane32_swap_b32_e32 v224, v226
	v_permlane32_swap_b32_e32 v225, v227
	global_store_dwordx4 v[244:245], v[224:227], off offset:128
	s_waitcnt vmcnt(7)
	v_permlane32_swap_b32_e32 v228, v230
	v_permlane32_swap_b32_e32 v229, v231
	v_mul_f32_e32 v64, v64, v77
	v_mul_f32_e32 v65, v65, v77
	v_lshlrev_b32_e32 v247, 16, v228
	v_mul_f32_e32 v64, v128, v64
	v_mul_f32_e32 v65, v129, v65
	v_and_b32_e32 v228, 0xffff0000, v228
	v_mul_f32_e32 v64, v64, v247
	v_mul_f32_e32 v65, v65, v228
	v_cvt_pk_bf16_f32 v228, v64, v65
	v_mul_f32_e32 v42, v42, v77
	v_mul_f32_e32 v43, v43, v77
	v_lshlrev_b32_e32 v247, 16, v229
	v_mul_f32_e32 v42, v130, v42
	v_mul_f32_e32 v43, v131, v43
	v_and_b32_e32 v229, 0xffff0000, v229
	v_mul_f32_e32 v42, v42, v247
	v_mul_f32_e32 v43, v43, v229
	v_cvt_pk_bf16_f32 v229, v42, v43
	v_mul_f32_e32 v38, v38, v77
	v_mul_f32_e32 v39, v39, v77
	v_lshlrev_b32_e32 v247, 16, v230
	v_mul_f32_e32 v38, v132, v38
	v_mul_f32_e32 v39, v133, v39
	v_and_b32_e32 v230, 0xffff0000, v230
	v_mul_f32_e32 v38, v38, v247
	v_mul_f32_e32 v39, v39, v230
	v_cvt_pk_bf16_f32 v230, v38, v39
	v_mul_f32_e32 v40, v40, v77
	v_mul_f32_e32 v41, v41, v77
	v_lshlrev_b32_e32 v247, 16, v231
	v_mul_f32_e32 v40, v134, v40
	v_mul_f32_e32 v41, v135, v41
	v_and_b32_e32 v231, 0xffff0000, v231
	v_mul_f32_e32 v40, v40, v247
	v_mul_f32_e32 v41, v41, v231
	v_cvt_pk_bf16_f32 v231, v40, v41
	s_nop 1
	v_permlane32_swap_b32_e32 v228, v230
	v_permlane32_swap_b32_e32 v229, v231
	global_store_dwordx4 v[244:245], v[228:231], off offset:160
	s_waitcnt vmcnt(7)
	v_permlane32_swap_b32_e32 v232, v234
	v_permlane32_swap_b32_e32 v233, v235
	v_mul_f32_e32 v46, v46, v77
	v_mul_f32_e32 v47, v47, v77
	v_lshlrev_b32_e32 v247, 16, v232
	v_mul_f32_e32 v46, v136, v46
	v_mul_f32_e32 v47, v137, v47
	v_and_b32_e32 v232, 0xffff0000, v232
	v_mul_f32_e32 v46, v46, v247
	v_mul_f32_e32 v47, v47, v232
	v_cvt_pk_bf16_f32 v232, v46, v47
	v_mul_f32_e32 v44, v44, v77
	v_mul_f32_e32 v45, v45, v77
	v_lshlrev_b32_e32 v247, 16, v233
	v_mul_f32_e32 v44, v138, v44
	v_mul_f32_e32 v45, v139, v45
	v_and_b32_e32 v233, 0xffff0000, v233
	v_mul_f32_e32 v44, v44, v247
	v_mul_f32_e32 v45, v45, v233
	v_cvt_pk_bf16_f32 v233, v44, v45
	v_mul_f32_e32 v18, v18, v77
	v_mul_f32_e32 v19, v19, v77
	v_lshlrev_b32_e32 v247, 16, v234
	v_mul_f32_e32 v18, v140, v18
	v_mul_f32_e32 v19, v141, v19
	v_and_b32_e32 v234, 0xffff0000, v234
	v_mul_f32_e32 v18, v18, v247
	v_mul_f32_e32 v19, v19, v234
	v_cvt_pk_bf16_f32 v234, v18, v19
	v_mul_f32_e32 v20, v20, v77
	v_mul_f32_e32 v21, v21, v77
	v_lshlrev_b32_e32 v247, 16, v235
	v_mul_f32_e32 v20, v142, v20
	v_mul_f32_e32 v21, v143, v21
	v_and_b32_e32 v235, 0xffff0000, v235
	v_mul_f32_e32 v20, v20, v247
	v_mul_f32_e32 v21, v21, v235
	v_cvt_pk_bf16_f32 v235, v20, v21
	s_nop 1
	v_permlane32_swap_b32_e32 v232, v234
	v_permlane32_swap_b32_e32 v233, v235
	global_store_dwordx4 v[244:245], v[232:235], off offset:192
	s_waitcnt vmcnt(7)
	v_permlane32_swap_b32_e32 v236, v238
	v_permlane32_swap_b32_e32 v237, v239
	v_mul_f32_e32 v26, v26, v77
	v_mul_f32_e32 v27, v27, v77
	v_lshlrev_b32_e32 v247, 16, v236
	v_mul_f32_e32 v26, v144, v26
	v_mul_f32_e32 v27, v145, v27
	v_and_b32_e32 v236, 0xffff0000, v236
	v_mul_f32_e32 v26, v26, v247
	v_mul_f32_e32 v27, v27, v236
	v_cvt_pk_bf16_f32 v236, v26, v27
	v_mul_f32_e32 v24, v24, v77
	v_mul_f32_e32 v25, v25, v77
	v_lshlrev_b32_e32 v247, 16, v237
	v_mul_f32_e32 v24, v146, v24
	v_mul_f32_e32 v25, v147, v25
	v_and_b32_e32 v237, 0xffff0000, v237
	v_mul_f32_e32 v24, v24, v247
	v_mul_f32_e32 v25, v25, v237
	v_cvt_pk_bf16_f32 v237, v24, v25
	v_mul_f32_e32 v22, v22, v77
	v_mul_f32_e32 v23, v23, v77
	v_lshlrev_b32_e32 v247, 16, v238
	v_mul_f32_e32 v22, v148, v22
	v_mul_f32_e32 v23, v149, v23
	v_and_b32_e32 v238, 0xffff0000, v238
	v_mul_f32_e32 v22, v22, v247
	v_mul_f32_e32 v23, v23, v238
	v_cvt_pk_bf16_f32 v238, v22, v23
	v_mul_f32_e32 v6, v6, v77
	v_mul_f32_e32 v7, v7, v77
	v_lshlrev_b32_e32 v247, 16, v239
	v_mul_f32_e32 v6, v150, v6
	v_mul_f32_e32 v7, v151, v7
	v_and_b32_e32 v239, 0xffff0000, v239
	v_mul_f32_e32 v6, v6, v247
	v_mul_f32_e32 v7, v7, v239
	v_cvt_pk_bf16_f32 v239, v6, v7
	s_nop 1
	v_permlane32_swap_b32_e32 v236, v238
	v_permlane32_swap_b32_e32 v237, v239
	global_store_dwordx4 v[244:245], v[236:239], off offset:224
